# v86 + nt (streaming) policy on the final phase's y stores (never re-read)
# speedup vs baseline: 1.0070x; 1.0041x over previous
.LBB0_29:
	s_waitcnt vmcnt(3)
	v_lshlrev_b32_e32 v44, 16, v20
	v_and_b32_e32 v45, 0xffff0000, v20
	v_lshlrev_b32_e32 v48, 16, v21
	v_and_b32_e32 v49, 0xffff0000, v21
	v_lshlrev_b32_e32 v184, 2, v16
	v_pk_mul_f32 v[44:45], v[46:47], v[44:45] op_sel_hi:[0,1]
	v_pk_mul_f32 v[48:49], v[46:47], v[48:49] op_sel_hi:[0,1]
	v_lshl_add_u64 v[40:41], v[40:41], 0, v[184:185]
	v_pk_mul_f32 v[50:51], v[2:3], v[48:49]
	v_pk_mul_f32 v[48:49], v[0:1], v[44:45]
	global_store_dwordx4 v[40:41], v[48:51], off nt
	s_waitcnt vmcnt(3)
	v_lshlrev_b32_e32 v44, 16, v22
	v_and_b32_e32 v45, 0xffff0000, v22
	v_lshlrev_b32_e32 v48, 16, v23
	v_and_b32_e32 v49, 0xffff0000, v23
	v_pk_mul_f32 v[44:45], v[46:47], v[44:45] op_sel_hi:[0,1]
	v_pk_mul_f32 v[48:49], v[46:47], v[48:49] op_sel_hi:[0,1]
	v_pk_mul_f32 v[50:51], v[6:7], v[48:49]
	v_pk_mul_f32 v[48:49], v[4:5], v[44:45]
	global_store_dwordx4 v[40:41], v[48:51], off offset:1024 nt
	s_waitcnt vmcnt(3)
	v_lshlrev_b32_e32 v44, 16, v24
	v_and_b32_e32 v45, 0xffff0000, v24
	v_lshlrev_b32_e32 v48, 16, v25
	v_and_b32_e32 v49, 0xffff0000, v25
	v_pk_mul_f32 v[44:45], v[46:47], v[44:45] op_sel_hi:[0,1]
	v_pk_mul_f32 v[48:49], v[46:47], v[48:49] op_sel_hi:[0,1]
	v_pk_mul_f32 v[50:51], v[10:11], v[48:49]
	v_pk_mul_f32 v[48:49], v[8:9], v[44:45]
	global_store_dwordx4 v[40:41], v[48:51], off offset:2048 nt
	s_waitcnt vmcnt(3)
	v_lshlrev_b32_e32 v44, 16, v28
	v_and_b32_e32 v45, 0xffff0000, v28
	v_lshlrev_b32_e32 v48, 16, v29
	v_and_b32_e32 v49, 0xffff0000, v29
	v_pk_mul_f32 v[44:45], v[46:47], v[44:45] op_sel_hi:[0,1]
	v_pk_mul_f32 v[46:47], v[46:47], v[48:49] op_sel_hi:[0,1]
	v_pk_mul_f32 v[46:47], v[14:15], v[46:47]
	v_pk_mul_f32 v[44:45], v[12:13], v[44:45]
	global_store_dwordx4 v[40:41], v[44:47], off offset:3072 nt
	s_or_b64 exec, exec, s[4:5]
	s_and_saveexec_b64 s[4:5], s[0:1]
	s_cbranch_execz .LBB0_15
	s_branch .LBB0_33

.LBB0_33:
	v_lshlrev_b32_e32 v184, 2, v16
	v_lshl_add_u64 v[44:45], v[38:39], 0, v[184:185]
	s_waitcnt vmcnt(3)
	v_lshlrev_b32_e32 v38, 16, v26
	v_and_b32_e32 v39, 0xffff0000, v26
	v_lshlrev_b32_e32 v40, 16, v27
	v_and_b32_e32 v41, 0xffff0000, v27
	v_pk_mul_f32 v[38:39], v[42:43], v[38:39] op_sel_hi:[0,1]
	v_pk_mul_f32 v[40:41], v[42:43], v[40:41] op_sel_hi:[0,1]
	v_pk_mul_f32 v[40:41], v[2:3], v[40:41]
	v_pk_mul_f32 v[38:39], v[0:1], v[38:39]
	global_store_dwordx4 v[44:45], v[38:41], off nt
	s_waitcnt vmcnt(3)
	s_nop 0
	v_lshlrev_b32_e32 v38, 16, v30
	v_and_b32_e32 v39, 0xffff0000, v30
	v_lshlrev_b32_e32 v40, 16, v31
	v_and_b32_e32 v41, 0xffff0000, v31
	v_pk_mul_f32 v[38:39], v[42:43], v[38:39] op_sel_hi:[0,1]
	v_pk_mul_f32 v[40:41], v[42:43], v[40:41] op_sel_hi:[0,1]
	v_pk_mul_f32 v[40:41], v[6:7], v[40:41]
	v_pk_mul_f32 v[38:39], v[4:5], v[38:39]
	global_store_dwordx4 v[44:45], v[38:41], off offset:1024 nt
	s_waitcnt vmcnt(3)
	s_nop 0
	v_lshlrev_b32_e32 v38, 16, v32
	v_and_b32_e32 v39, 0xffff0000, v32
	v_lshlrev_b32_e32 v40, 16, v33
	v_and_b32_e32 v41, 0xffff0000, v33
	v_pk_mul_f32 v[38:39], v[42:43], v[38:39] op_sel_hi:[0,1]
	v_pk_mul_f32 v[40:41], v[42:43], v[40:41] op_sel_hi:[0,1]
	v_pk_mul_f32 v[40:41], v[10:11], v[40:41]
	v_pk_mul_f32 v[38:39], v[8:9], v[38:39]
	global_store_dwordx4 v[44:45], v[38:41], off offset:2048 nt
	s_waitcnt vmcnt(3)
	s_nop 0
	v_lshlrev_b32_e32 v38, 16, v34
	v_and_b32_e32 v39, 0xffff0000, v34
	v_lshlrev_b32_e32 v40, 16, v35
	v_and_b32_e32 v41, 0xffff0000, v35
	v_pk_mul_f32 v[38:39], v[42:43], v[38:39] op_sel_hi:[0,1]
	v_pk_mul_f32 v[40:41], v[42:43], v[40:41] op_sel_hi:[0,1]
	v_pk_mul_f32 v[40:41], v[14:15], v[40:41]
	v_pk_mul_f32 v[38:39], v[12:13], v[38:39]
	global_store_dwordx4 v[44:45], v[38:41], off offset:3072 nt
	s_branch .LBB0_15
